# int8 epilogue: 48 in-place v_cvt_f32_i32 moved into the shadow of the two LDS waits at the epilogue start (wait placement)
# baseline (speedup 1.0000x reference)
.LBB0_297:
	v_mov_b32_e32 v132, v240
	v_cvt_f32_i32_e32 v125, v125
	v_readfirstlane_b32 s17, v132
	s_ashr_i32 s21, s17, 2
	s_lshr_b32 s17, s17, 1
	s_and_b32 s17, s17, 0x60
	v_and_b32_e32 v166, 15, v132
	v_lshrrev_b32_e32 v132, 1, v132
	s_lshl_b32 s27, s17, 2
	v_and_b32_e32 v167, 24, v132
	s_add_i32 s27, s27, 0
	v_lshl_add_u32 v132, v167, 2, s27
	v_add_u32_e32 v140, 0x21600, v132
	ds_read_b128 v[132:135], v140 offset:512
	ds_read_b128 v[136:139], v140 offset:528
	s_andn2_b32 s21, s21, 63
	ds_read_b128 v[158:161], v140
	ds_read_b128 v[162:165], v140 offset:16
	s_lshl_b32 s27, s21, 2
	s_add_i32 s27, s27, 0
	v_lshl_add_u32 v140, v166, 2, s27
	v_cvt_f32_i32_e32 v124, v124
	v_cvt_f32_i32_e32 v127, v127
	v_cvt_f32_i32_e32 v126, v126
	v_cvt_f32_i32_e32 v119, v119
	v_cvt_f32_i32_e32 v118, v118
	v_cvt_f32_i32_e32 v113, v113
	v_cvt_f32_i32_e32 v112, v112
	v_cvt_f32_i32_e32 v109, v109
	v_cvt_f32_i32_e32 v108, v108
	v_cvt_f32_i32_e32 v110, v110
	v_cvt_f32_i32_e32 v103, v103
	v_cvt_f32_i32_e32 v102, v102
	v_cvt_f32_i32_e32 v97, v97
	v_cvt_f32_i32_e32 v96, v96
	v_cvt_f32_i32_e32 v93, v93
	v_cvt_f32_i32_e32 v92, v92
	v_cvt_f32_i32_e32 v94, v94
	v_cvt_f32_i32_e32 v87, v87
	v_cvt_f32_i32_e32 v86, v86
	v_cvt_f32_i32_e32 v81, v81
	v_cvt_f32_i32_e32 v80, v80
	v_cvt_f32_i32_e32 v77, v77
	v_cvt_f32_i32_e32 v76, v76
	v_cvt_f32_i32_e32 v78, v78
	v_cvt_f32_i32_e32 v71, v71
	v_cvt_f32_i32_e32 v70, v70
	v_cvt_f32_i32_e32 v61, v61
	v_cvt_f32_i32_e32 v60, v60
	v_cvt_f32_i32_e32 v67, v67
	v_cvt_f32_i32_e32 v66, v66
	v_cvt_f32_i32_e32 v63, v63
	v_cvt_f32_i32_e32 v62, v62
	s_waitcnt lgkmcnt(0)
	v_pk_mul_f32 v[132:133], v[216:217], v[132:133]
	v_add_u32_e32 v140, 0x21200, v140
	v_pk_mul_f32 v[150:151], v[158:159], s[48:49] op_sel_hi:[1,0]
	v_pk_mul_f32 v[146:147], v[158:159], v[132:133]
	v_cvt_f32_i32_e32 v159, v129
	v_cvt_f32_i32_e32 v158, v128
	v_mov_b32_e32 v197, v196
	ds_read2_b32 v[156:157], v140 offset1:16
	ds_read2_b32 v[154:155], v140 offset0:32 offset1:48
	ds_read2_b32 v[152:153], v140 offset0:128 offset1:144
	ds_read2_b32 v[148:149], v140 offset0:160 offset1:176
	v_pk_mul_f32 v[138:139], v[196:197], v[138:139]
	v_pk_mul_f32 v[136:137], v[216:217], v[136:137]
	v_pk_mul_f32 v[134:135], v[196:197], v[134:135]
	v_cvt_f32_i32_e32 v131, v131
	v_cvt_f32_i32_e32 v130, v130
	v_pk_mul_f32 v[142:143], v[160:161], v[134:135]
	v_pk_mul_f32 v[144:145], v[160:161], s[48:49] op_sel_hi:[1,0]
	v_pk_mul_f32 v[140:141], v[162:163], s[48:49] op_sel_hi:[1,0]
	v_pk_mul_f32 v[134:135], v[164:165], v[138:139]
	v_pk_mul_f32 v[138:139], v[162:163], v[136:137]
	v_cvt_f32_i32_e32 v55, v55
	v_cvt_f32_i32_e32 v54, v54
	v_cvt_f32_i32_e32 v49, v49
	v_cvt_f32_i32_e32 v48, v48
	v_cvt_f32_i32_e32 v45, v45
	v_cvt_f32_i32_e32 v44, v44
	v_cvt_f32_i32_e32 v46, v46
	v_cvt_f32_i32_e32 v39, v39
	v_cvt_f32_i32_e32 v38, v38
	v_cvt_f32_i32_e32 v31, v31
	v_cvt_f32_i32_e32 v30, v30
	v_cvt_f32_i32_e32 v27, v27
	v_cvt_f32_i32_e32 v26, v26
	v_cvt_f32_i32_e32 v28, v28
	v_cvt_f32_i32_e32 v21, v21
	v_cvt_f32_i32_e32 v20, v20
	s_waitcnt lgkmcnt(0)
	v_pk_mul_f32 v[160:161], v[150:151], v[156:157] op_sel_hi:[1,0]
	v_mul_f32_e32 v162, v156, v156
	v_pk_mul_f32 v[160:161], v[160:161], v[158:159]
	v_pk_mul_f32 v[124:125], v[158:159], v[124:125]
	v_pk_mul_f32 v[158:159], v[146:147], v[162:163] op_sel_hi:[1,0]
	v_pk_mul_f32 v[126:127], v[130:131], v[126:127]
	v_pk_mul_f32 v[124:125], v[124:125], v[158:159]
	v_pk_mul_f32 v[158:159], v[144:145], v[156:157] op_sel_hi:[1,0]
	v_cvt_f32_i32_e32 v117, v117
	v_pk_mul_f32 v[158:159], v[158:159], v[130:131]
	v_cvt_f32_i32_e32 v131, v121
	v_cvt_f32_i32_e32 v130, v120
	v_pk_mul_f32 v[120:121], v[142:143], v[162:163] op_sel_hi:[1,0]
	v_cvt_f32_i32_e32 v116, v116
	v_pk_mul_f32 v[120:121], v[126:127], v[120:121]
	v_pk_mul_f32 v[126:127], v[140:141], v[156:157] op_sel_hi:[1,0]
	v_cvt_f32_i32_e32 v123, v123
	v_pk_mul_f32 v[126:127], v[126:127], v[130:131]
	v_cvt_f32_i32_e32 v122, v122
	v_exp_f32_e32 v126, v126
	v_exp_f32_e32 v127, v127
	v_pk_mul_f32 v[136:137], v[164:165], s[48:49] op_sel_hi:[1,0]
	v_pk_mul_f32 v[116:117], v[130:131], v[116:117]
	v_pk_mul_f32 v[130:131], v[138:139], v[162:163] op_sel_hi:[1,0]
	v_pk_add_f32 v[126:127], v[126:127], 1.0 op_sel_hi:[1,0]
	v_pk_mul_f32 v[116:117], v[116:117], v[130:131]
	v_pk_mul_f32 v[130:131], v[136:137], v[156:157] op_sel_hi:[1,0]
	v_exp_f32_e32 v160, v160
	v_pk_mul_f32 v[130:131], v[130:131], v[122:123]
	v_exp_f32_e32 v161, v161
	v_exp_f32_e32 v158, v158
	v_exp_f32_e32 v159, v159
	v_rcp_f32_e32 v126, v126
	v_rcp_f32_e32 v127, v127
	v_exp_f32_e32 v130, v130
	v_exp_f32_e32 v131, v131
	v_pk_add_f32 v[160:161], v[160:161], 1.0 op_sel_hi:[1,0]
	v_pk_add_f32 v[158:159], v[158:159], 1.0 op_sel_hi:[1,0]
	v_pk_mul_f32 v[116:117], v[116:117], v[126:127]
	v_pk_add_f32 v[126:127], v[130:131], 1.0 op_sel_hi:[1,0]
	v_rcp_f32_e32 v160, v160
	v_rcp_f32_e32 v161, v161
	v_rcp_f32_e32 v158, v158
	v_rcp_f32_e32 v159, v159
	v_rcp_f32_e32 v126, v126
	v_rcp_f32_e32 v127, v127
	v_or_b32_e32 v132, s30, v167
	v_pk_mul_f32 v[118:119], v[122:123], v[118:119]
	v_pk_mul_f32 v[122:123], v[134:135], v[162:163] op_sel_hi:[1,0]
	v_or_b32_e32 v132, s17, v132
	v_or_b32_e32 v133, s21, v166
	v_pk_mul_f32 v[118:119], v[118:119], v[122:123]
	v_cndmask_b32_e64 v122, 0, 1, s[4:5]
	v_lshl_add_u32 v128, s26, 8, v133
	v_ashrrev_i32_e32 v133, 31, v132
	v_pk_mul_f32 v[124:125], v[124:125], v[160:161]
	v_pk_mul_f32 v[120:121], v[120:121], v[158:159]
	v_pk_mul_f32 v[118:119], v[118:119], v[126:127]
	v_cmp_ne_u32_e64 s[42:43], 1, v122
	s_andn2_b64 vcc, exec, s[4:5]
	s_mov_b64 s[26:27], -1
	s_cbranch_vccnz .LBB0_299
	v_cvt_pk_fp8_f32 v122, v124, v125
	v_cvt_pk_fp8_f32 v123, v116, v117
	v_mad_u32_u24 v126, v128, s92, v132
	v_cvt_pk_fp8_f32 v122, v120, v121 op_sel:[0,0,1]
	v_cvt_pk_fp8_f32 v123, v118, v119 op_sel:[0,0,1]
	s_mov_b64 s[26:27], 0
	global_store_dwordx2 v126, v[122:123], s[8:9]

.LBB0_301:
	v_mov_b32_e32 v116, v157
	v_pk_mul_f32 v[118:119], v[150:151], v[116:117] op_sel_hi:[1,0]
	v_cvt_f32_i32_e32 v111, v111
	v_pk_mul_f32 v[118:119], v[118:119], v[112:113]
	v_pk_mul_f32 v[108:109], v[112:113], v[108:109]
	v_cvt_f32_i32_e32 v113, v115
	v_cvt_f32_i32_e32 v112, v114
	v_mul_f32_e32 v120, v157, v157
	v_pk_mul_f32 v[114:115], v[146:147], v[120:121] op_sel_hi:[1,0]
	v_cvt_f32_i32_e32 v101, v101
	v_pk_mul_f32 v[108:109], v[108:109], v[114:115]
	v_pk_mul_f32 v[114:115], v[144:145], v[116:117] op_sel_hi:[1,0]
	v_pk_mul_f32 v[110:111], v[112:113], v[110:111]
	v_pk_mul_f32 v[114:115], v[114:115], v[112:113]
	v_cvt_f32_i32_e32 v113, v105
	v_cvt_f32_i32_e32 v112, v104
	v_pk_mul_f32 v[104:105], v[142:143], v[120:121] op_sel_hi:[1,0]
	v_cvt_f32_i32_e32 v100, v100
	v_pk_mul_f32 v[104:105], v[110:111], v[104:105]
	v_pk_mul_f32 v[110:111], v[140:141], v[116:117] op_sel_hi:[1,0]
	v_cvt_f32_i32_e32 v107, v107
	v_pk_mul_f32 v[110:111], v[110:111], v[112:113]
	v_cvt_f32_i32_e32 v106, v106
	v_exp_f32_e32 v110, v110
	v_exp_f32_e32 v111, v111
	v_pk_mul_f32 v[100:101], v[112:113], v[100:101]
	v_pk_mul_f32 v[112:113], v[138:139], v[120:121] op_sel_hi:[1,0]
	v_exp_f32_e32 v118, v118
	v_pk_mul_f32 v[100:101], v[100:101], v[112:113]
	v_pk_mul_f32 v[112:113], v[136:137], v[116:117] op_sel_hi:[1,0]
	v_pk_add_f32 v[110:111], v[110:111], 1.0 op_sel_hi:[1,0]
	v_pk_mul_f32 v[112:113], v[112:113], v[106:107]
	v_exp_f32_e32 v119, v119
	v_exp_f32_e32 v114, v114
	v_exp_f32_e32 v115, v115
	v_rcp_f32_e32 v110, v110
	v_rcp_f32_e32 v111, v111
	v_exp_f32_e32 v112, v112
	v_exp_f32_e32 v113, v113
	v_pk_add_f32 v[118:119], v[118:119], 1.0 op_sel_hi:[1,0]
	v_pk_add_f32 v[114:115], v[114:115], 1.0 op_sel_hi:[1,0]
	v_pk_mul_f32 v[100:101], v[100:101], v[110:111]
	v_pk_add_f32 v[110:111], v[112:113], 1.0 op_sel_hi:[1,0]
	v_rcp_f32_e32 v118, v118
	v_rcp_f32_e32 v119, v119
	v_rcp_f32_e32 v114, v114
	v_rcp_f32_e32 v115, v115
	v_rcp_f32_e32 v110, v110
	v_rcp_f32_e32 v111, v111
	v_pk_mul_f32 v[102:103], v[106:107], v[102:103]
	v_pk_mul_f32 v[106:107], v[134:135], v[120:121] op_sel_hi:[1,0]
	v_pk_mul_f32 v[108:109], v[108:109], v[118:119]
	v_pk_mul_f32 v[102:103], v[102:103], v[106:107]
	v_pk_mul_f32 v[104:105], v[104:105], v[114:115]
	v_pk_mul_f32 v[102:103], v[102:103], v[110:111]
	v_or_b32_e32 v106, 16, v128
	s_and_b64 vcc, exec, s[42:43]
	s_mov_b64 s[26:27], -1
	s_cbranch_vccnz .LBB0_303
	v_cvt_pk_fp8_f32 v110, v108, v109
	v_cvt_pk_fp8_f32 v111, v100, v101
	v_mad_u32_u24 v112, v106, s92, v132
	v_cvt_pk_fp8_f32 v110, v104, v105 op_sel:[0,0,1]
	v_cvt_pk_fp8_f32 v111, v102, v103 op_sel:[0,0,1]
	s_mov_b64 s[26:27], 0
	global_store_dwordx2 v112, v[110:111], s[8:9]

.LBB0_305:
	v_pk_mul_f32 v[100:101], v[150:151], v[154:155] op_sel_hi:[1,0]
	v_cvt_f32_i32_e32 v95, v95
	v_pk_mul_f32 v[100:101], v[100:101], v[96:97]
	v_pk_mul_f32 v[92:93], v[96:97], v[92:93]
	v_cvt_f32_i32_e32 v97, v99
	v_cvt_f32_i32_e32 v96, v98
	v_mul_f32_e32 v102, v154, v154
	v_pk_mul_f32 v[98:99], v[146:147], v[102:103] op_sel_hi:[1,0]
	v_cvt_f32_i32_e32 v85, v85
	v_pk_mul_f32 v[92:93], v[92:93], v[98:99]
	v_pk_mul_f32 v[98:99], v[144:145], v[154:155] op_sel_hi:[1,0]
	v_pk_mul_f32 v[94:95], v[96:97], v[94:95]
	v_pk_mul_f32 v[98:99], v[98:99], v[96:97]
	v_cvt_f32_i32_e32 v97, v89
	v_cvt_f32_i32_e32 v96, v88
	v_pk_mul_f32 v[88:89], v[142:143], v[102:103] op_sel_hi:[1,0]
	v_cvt_f32_i32_e32 v84, v84
	v_pk_mul_f32 v[88:89], v[94:95], v[88:89]
	v_pk_mul_f32 v[94:95], v[140:141], v[154:155] op_sel_hi:[1,0]
	v_cvt_f32_i32_e32 v91, v91
	v_pk_mul_f32 v[94:95], v[94:95], v[96:97]
	v_cvt_f32_i32_e32 v90, v90
	v_exp_f32_e32 v94, v94
	v_exp_f32_e32 v95, v95
	v_pk_mul_f32 v[84:85], v[96:97], v[84:85]
	v_pk_mul_f32 v[96:97], v[138:139], v[102:103] op_sel_hi:[1,0]
	v_exp_f32_e32 v100, v100
	v_pk_mul_f32 v[84:85], v[84:85], v[96:97]
	v_pk_mul_f32 v[96:97], v[136:137], v[154:155] op_sel_hi:[1,0]
	v_pk_add_f32 v[94:95], v[94:95], 1.0 op_sel_hi:[1,0]
	v_pk_mul_f32 v[96:97], v[96:97], v[90:91]
	v_exp_f32_e32 v101, v101
	v_exp_f32_e32 v98, v98
	v_exp_f32_e32 v99, v99
	v_rcp_f32_e32 v94, v94
	v_rcp_f32_e32 v95, v95
	v_exp_f32_e32 v96, v96
	v_exp_f32_e32 v97, v97
	v_pk_add_f32 v[100:101], v[100:101], 1.0 op_sel_hi:[1,0]
	v_pk_add_f32 v[98:99], v[98:99], 1.0 op_sel_hi:[1,0]
	v_pk_mul_f32 v[84:85], v[84:85], v[94:95]
	v_pk_add_f32 v[94:95], v[96:97], 1.0 op_sel_hi:[1,0]
	v_rcp_f32_e32 v100, v100
	v_rcp_f32_e32 v101, v101
	v_rcp_f32_e32 v98, v98
	v_rcp_f32_e32 v99, v99
	v_rcp_f32_e32 v94, v94
	v_rcp_f32_e32 v95, v95
	v_pk_mul_f32 v[86:87], v[90:91], v[86:87]
	v_pk_mul_f32 v[90:91], v[134:135], v[102:103] op_sel_hi:[1,0]
	v_pk_mul_f32 v[92:93], v[92:93], v[100:101]
	v_pk_mul_f32 v[86:87], v[86:87], v[90:91]
	v_pk_mul_f32 v[88:89], v[88:89], v[98:99]
	v_pk_mul_f32 v[86:87], v[86:87], v[94:95]
	v_or_b32_e32 v90, 32, v128
	s_and_b64 vcc, exec, s[42:43]
	s_mov_b64 s[26:27], -1
	s_cbranch_vccnz .LBB0_307
	v_cvt_pk_fp8_f32 v94, v92, v93
	v_cvt_pk_fp8_f32 v95, v84, v85
	v_mad_u32_u24 v96, v90, s92, v132
	v_cvt_pk_fp8_f32 v94, v88, v89 op_sel:[0,0,1]
	v_cvt_pk_fp8_f32 v95, v86, v87 op_sel:[0,0,1]
	s_mov_b64 s[26:27], 0
	global_store_dwordx2 v96, v[94:95], s[8:9]

.LBB0_309:
	v_mov_b32_e32 v84, v155
	v_pk_mul_f32 v[86:87], v[150:151], v[84:85] op_sel_hi:[1,0]
	v_cvt_f32_i32_e32 v79, v79
	v_pk_mul_f32 v[86:87], v[86:87], v[80:81]
	v_pk_mul_f32 v[76:77], v[80:81], v[76:77]
	v_cvt_f32_i32_e32 v81, v83
	v_cvt_f32_i32_e32 v80, v82
	v_mul_f32_e32 v88, v155, v155
	v_pk_mul_f32 v[82:83], v[146:147], v[88:89] op_sel_hi:[1,0]
	v_cvt_f32_i32_e32 v69, v69
	v_pk_mul_f32 v[76:77], v[76:77], v[82:83]
	v_pk_mul_f32 v[82:83], v[144:145], v[84:85] op_sel_hi:[1,0]
	v_pk_mul_f32 v[78:79], v[80:81], v[78:79]
	v_pk_mul_f32 v[82:83], v[82:83], v[80:81]
	v_cvt_f32_i32_e32 v81, v73
	v_cvt_f32_i32_e32 v80, v72
	v_pk_mul_f32 v[72:73], v[142:143], v[88:89] op_sel_hi:[1,0]
	v_cvt_f32_i32_e32 v68, v68
	v_pk_mul_f32 v[72:73], v[78:79], v[72:73]
	v_pk_mul_f32 v[78:79], v[140:141], v[84:85] op_sel_hi:[1,0]
	v_cvt_f32_i32_e32 v75, v75
	v_pk_mul_f32 v[78:79], v[78:79], v[80:81]
	v_cvt_f32_i32_e32 v74, v74
	v_exp_f32_e32 v78, v78
	v_exp_f32_e32 v79, v79
	v_pk_mul_f32 v[68:69], v[80:81], v[68:69]
	v_pk_mul_f32 v[80:81], v[138:139], v[88:89] op_sel_hi:[1,0]
	v_exp_f32_e32 v86, v86
	v_pk_mul_f32 v[68:69], v[68:69], v[80:81]
	v_pk_mul_f32 v[80:81], v[136:137], v[84:85] op_sel_hi:[1,0]
	v_pk_add_f32 v[78:79], v[78:79], 1.0 op_sel_hi:[1,0]
	v_pk_mul_f32 v[80:81], v[80:81], v[74:75]
	v_exp_f32_e32 v87, v87
	v_exp_f32_e32 v82, v82
	v_exp_f32_e32 v83, v83
	v_rcp_f32_e32 v78, v78
	v_rcp_f32_e32 v79, v79
	v_exp_f32_e32 v80, v80
	v_exp_f32_e32 v81, v81
	v_pk_add_f32 v[86:87], v[86:87], 1.0 op_sel_hi:[1,0]
	v_pk_add_f32 v[82:83], v[82:83], 1.0 op_sel_hi:[1,0]
	v_pk_mul_f32 v[68:69], v[68:69], v[78:79]
	v_pk_add_f32 v[78:79], v[80:81], 1.0 op_sel_hi:[1,0]
	v_rcp_f32_e32 v86, v86
	v_rcp_f32_e32 v87, v87
	v_rcp_f32_e32 v82, v82
	v_rcp_f32_e32 v83, v83
	v_rcp_f32_e32 v78, v78
	v_rcp_f32_e32 v79, v79
	v_pk_mul_f32 v[70:71], v[74:75], v[70:71]
	v_pk_mul_f32 v[74:75], v[134:135], v[88:89] op_sel_hi:[1,0]
	v_pk_mul_f32 v[76:77], v[76:77], v[86:87]
	v_pk_mul_f32 v[70:71], v[70:71], v[74:75]
	v_pk_mul_f32 v[72:73], v[72:73], v[82:83]
	v_pk_mul_f32 v[70:71], v[70:71], v[78:79]
	v_or_b32_e32 v74, 48, v128
	s_and_b64 vcc, exec, s[42:43]
	s_mov_b64 s[26:27], -1
	s_cbranch_vccnz .LBB0_311
	v_cvt_pk_fp8_f32 v78, v76, v77
	v_cvt_pk_fp8_f32 v79, v68, v69
	v_mad_u32_u24 v80, v74, s92, v132
	v_cvt_pk_fp8_f32 v78, v72, v73 op_sel:[0,0,1]
	v_cvt_pk_fp8_f32 v79, v70, v71 op_sel:[0,0,1]
	s_mov_b64 s[26:27], 0
	global_store_dwordx2 v80, v[78:79], s[8:9]

.LBB0_313:
	v_cvt_f32_i32_e32 v69, v65
	v_cvt_f32_i32_e32 v68, v64
	v_pk_mul_f32 v[70:71], v[150:151], v[152:153] op_sel_hi:[1,0]
	v_mul_f32_e32 v72, v152, v152
	v_pk_mul_f32 v[70:71], v[70:71], v[68:69]
	v_pk_mul_f32 v[60:61], v[68:69], v[60:61]
	v_pk_mul_f32 v[68:69], v[146:147], v[72:73] op_sel_hi:[1,0]
	v_pk_mul_f32 v[62:63], v[66:67], v[62:63]
	v_pk_mul_f32 v[60:61], v[60:61], v[68:69]
	v_pk_mul_f32 v[68:69], v[144:145], v[152:153] op_sel_hi:[1,0]
	v_cvt_f32_i32_e32 v53, v53
	v_pk_mul_f32 v[68:69], v[68:69], v[66:67]
	v_cvt_f32_i32_e32 v67, v57
	v_cvt_f32_i32_e32 v66, v56
	v_pk_mul_f32 v[56:57], v[142:143], v[72:73] op_sel_hi:[1,0]
	v_cvt_f32_i32_e32 v52, v52
	v_pk_mul_f32 v[56:57], v[62:63], v[56:57]
	v_pk_mul_f32 v[62:63], v[140:141], v[152:153] op_sel_hi:[1,0]
	v_cvt_f32_i32_e32 v59, v59
	v_pk_mul_f32 v[62:63], v[62:63], v[66:67]
	v_cvt_f32_i32_e32 v58, v58
	v_exp_f32_e32 v62, v62
	v_exp_f32_e32 v63, v63
	v_pk_mul_f32 v[52:53], v[66:67], v[52:53]
	v_pk_mul_f32 v[66:67], v[138:139], v[72:73] op_sel_hi:[1,0]
	v_exp_f32_e32 v70, v70
	v_pk_mul_f32 v[52:53], v[52:53], v[66:67]
	v_pk_mul_f32 v[66:67], v[136:137], v[152:153] op_sel_hi:[1,0]
	v_pk_add_f32 v[62:63], v[62:63], 1.0 op_sel_hi:[1,0]
	v_pk_mul_f32 v[66:67], v[66:67], v[58:59]
	v_exp_f32_e32 v71, v71
	v_exp_f32_e32 v68, v68
	v_exp_f32_e32 v69, v69
	v_rcp_f32_e32 v62, v62
	v_rcp_f32_e32 v63, v63
	v_exp_f32_e32 v66, v66
	v_exp_f32_e32 v67, v67
	v_pk_add_f32 v[70:71], v[70:71], 1.0 op_sel_hi:[1,0]
	v_pk_add_f32 v[68:69], v[68:69], 1.0 op_sel_hi:[1,0]
	v_pk_mul_f32 v[52:53], v[52:53], v[62:63]
	v_pk_add_f32 v[62:63], v[66:67], 1.0 op_sel_hi:[1,0]
	v_rcp_f32_e32 v70, v70
	v_rcp_f32_e32 v71, v71
	v_rcp_f32_e32 v68, v68
	v_rcp_f32_e32 v69, v69
	v_rcp_f32_e32 v62, v62
	v_rcp_f32_e32 v63, v63
	v_pk_mul_f32 v[54:55], v[58:59], v[54:55]
	v_pk_mul_f32 v[58:59], v[134:135], v[72:73] op_sel_hi:[1,0]
	v_add_u32_e32 v64, 0x80, v128
	v_pk_mul_f32 v[54:55], v[54:55], v[58:59]
	v_pk_mul_f32 v[60:61], v[60:61], v[70:71]
	v_pk_mul_f32 v[56:57], v[56:57], v[68:69]
	v_pk_mul_f32 v[54:55], v[54:55], v[62:63]
	s_and_b64 vcc, exec, s[42:43]
	s_mov_b64 s[26:27], -1
	s_cbranch_vccnz .LBB0_315
	v_cvt_pk_fp8_f32 v58, v60, v61
	v_cvt_pk_fp8_f32 v59, v52, v53
	v_mad_u32_u24 v62, v64, s92, v132
	v_cvt_pk_fp8_f32 v58, v56, v57 op_sel:[0,0,1]
	v_cvt_pk_fp8_f32 v59, v54, v55 op_sel:[0,0,1]
	s_mov_b64 s[26:27], 0
	global_store_dwordx2 v62, v[58:59], s[8:9]

.LBB0_317:
	v_mov_b32_e32 v52, v153
	v_pk_mul_f32 v[54:55], v[150:151], v[52:53] op_sel_hi:[1,0]
	v_cvt_f32_i32_e32 v47, v47
	v_pk_mul_f32 v[54:55], v[54:55], v[48:49]
	v_pk_mul_f32 v[44:45], v[48:49], v[44:45]
	v_cvt_f32_i32_e32 v49, v51
	v_cvt_f32_i32_e32 v48, v50
	v_mul_f32_e32 v56, v153, v153
	v_pk_mul_f32 v[50:51], v[146:147], v[56:57] op_sel_hi:[1,0]
	v_cvt_f32_i32_e32 v37, v37
	v_pk_mul_f32 v[44:45], v[44:45], v[50:51]
	v_pk_mul_f32 v[50:51], v[144:145], v[52:53] op_sel_hi:[1,0]
	v_pk_mul_f32 v[46:47], v[48:49], v[46:47]
	v_pk_mul_f32 v[50:51], v[50:51], v[48:49]
	v_cvt_f32_i32_e32 v49, v41
	v_cvt_f32_i32_e32 v48, v40
	v_pk_mul_f32 v[40:41], v[142:143], v[56:57] op_sel_hi:[1,0]
	v_cvt_f32_i32_e32 v36, v36
	v_pk_mul_f32 v[40:41], v[46:47], v[40:41]
	v_pk_mul_f32 v[46:47], v[140:141], v[52:53] op_sel_hi:[1,0]
	v_cvt_f32_i32_e32 v43, v43
	v_pk_mul_f32 v[46:47], v[46:47], v[48:49]
	v_cvt_f32_i32_e32 v42, v42
	v_exp_f32_e32 v46, v46
	v_exp_f32_e32 v47, v47
	v_pk_mul_f32 v[36:37], v[48:49], v[36:37]
	v_pk_mul_f32 v[48:49], v[138:139], v[56:57] op_sel_hi:[1,0]
	v_exp_f32_e32 v54, v54
	v_pk_mul_f32 v[36:37], v[36:37], v[48:49]
	v_pk_mul_f32 v[48:49], v[136:137], v[52:53] op_sel_hi:[1,0]
	v_pk_add_f32 v[46:47], v[46:47], 1.0 op_sel_hi:[1,0]
	v_pk_mul_f32 v[48:49], v[48:49], v[42:43]
	v_exp_f32_e32 v55, v55
	v_exp_f32_e32 v50, v50
	v_exp_f32_e32 v51, v51
	v_rcp_f32_e32 v46, v46
	v_rcp_f32_e32 v47, v47
	v_exp_f32_e32 v48, v48
	v_exp_f32_e32 v49, v49
	v_pk_add_f32 v[54:55], v[54:55], 1.0 op_sel_hi:[1,0]
	v_pk_add_f32 v[50:51], v[50:51], 1.0 op_sel_hi:[1,0]
	v_pk_mul_f32 v[36:37], v[36:37], v[46:47]
	v_pk_add_f32 v[46:47], v[48:49], 1.0 op_sel_hi:[1,0]
	v_rcp_f32_e32 v54, v54
	v_rcp_f32_e32 v55, v55
	v_rcp_f32_e32 v50, v50
	v_rcp_f32_e32 v51, v51
	v_rcp_f32_e32 v46, v46
	v_rcp_f32_e32 v47, v47
	v_pk_mul_f32 v[38:39], v[42:43], v[38:39]
	v_pk_mul_f32 v[42:43], v[134:135], v[56:57] op_sel_hi:[1,0]
	v_pk_mul_f32 v[44:45], v[44:45], v[54:55]
	v_pk_mul_f32 v[38:39], v[38:39], v[42:43]
	v_pk_mul_f32 v[40:41], v[40:41], v[50:51]
	v_pk_mul_f32 v[38:39], v[38:39], v[46:47]
	v_add_u32_e32 v42, 0x90, v128
	s_and_b64 vcc, exec, s[42:43]
	s_mov_b64 s[26:27], -1
	s_cbranch_vccnz .LBB0_319
	v_cvt_pk_fp8_f32 v46, v44, v45
	v_cvt_pk_fp8_f32 v47, v36, v37
	v_mad_u32_u24 v48, v42, s92, v132
	v_cvt_pk_fp8_f32 v46, v40, v41 op_sel:[0,0,1]
	v_cvt_pk_fp8_f32 v47, v38, v39 op_sel:[0,0,1]
	s_mov_b64 s[26:27], 0
	global_store_dwordx2 v48, v[46:47], s[8:9]

.LBB0_321:
	v_pk_mul_f32 v[36:37], v[150:151], v[148:149] op_sel_hi:[1,0]
	v_cvt_f32_i32_e32 v29, v29
	v_pk_mul_f32 v[36:37], v[36:37], v[30:31]
	v_pk_mul_f32 v[26:27], v[30:31], v[26:27]
	v_cvt_f32_i32_e32 v31, v33
	v_cvt_f32_i32_e32 v30, v32
	v_mul_f32_e32 v38, v148, v148
	v_pk_mul_f32 v[32:33], v[146:147], v[38:39] op_sel_hi:[1,0]
	v_cvt_f32_i32_e32 v19, v19
	v_pk_mul_f32 v[26:27], v[26:27], v[32:33]
	v_pk_mul_f32 v[32:33], v[144:145], v[148:149] op_sel_hi:[1,0]
	v_pk_mul_f32 v[28:29], v[30:31], v[28:29]
	v_pk_mul_f32 v[32:33], v[32:33], v[30:31]
	v_cvt_f32_i32_e32 v31, v23
	v_cvt_f32_i32_e32 v30, v22
	v_pk_mul_f32 v[22:23], v[142:143], v[38:39] op_sel_hi:[1,0]
	v_cvt_f32_i32_e32 v18, v18
	v_pk_mul_f32 v[22:23], v[28:29], v[22:23]
	v_pk_mul_f32 v[28:29], v[140:141], v[148:149] op_sel_hi:[1,0]
	v_cvt_f32_i32_e32 v25, v25
	v_pk_mul_f32 v[28:29], v[28:29], v[30:31]
	v_cvt_f32_i32_e32 v24, v24
	v_exp_f32_e32 v28, v28
	v_exp_f32_e32 v29, v29
	v_pk_mul_f32 v[18:19], v[30:31], v[18:19]
	v_pk_mul_f32 v[30:31], v[138:139], v[38:39] op_sel_hi:[1,0]
	v_exp_f32_e32 v36, v36
	v_pk_mul_f32 v[18:19], v[18:19], v[30:31]
	v_pk_mul_f32 v[30:31], v[136:137], v[148:149] op_sel_hi:[1,0]
	v_pk_add_f32 v[28:29], v[28:29], 1.0 op_sel_hi:[1,0]
	v_pk_mul_f32 v[30:31], v[30:31], v[24:25]
	v_exp_f32_e32 v37, v37
	v_exp_f32_e32 v32, v32
	v_exp_f32_e32 v33, v33
	v_rcp_f32_e32 v28, v28
	v_rcp_f32_e32 v29, v29
	v_exp_f32_e32 v30, v30
	v_exp_f32_e32 v31, v31
	v_pk_add_f32 v[36:37], v[36:37], 1.0 op_sel_hi:[1,0]
	v_pk_add_f32 v[32:33], v[32:33], 1.0 op_sel_hi:[1,0]
	v_pk_mul_f32 v[18:19], v[18:19], v[28:29]
	v_pk_add_f32 v[28:29], v[30:31], 1.0 op_sel_hi:[1,0]
	v_rcp_f32_e32 v36, v36
	v_rcp_f32_e32 v37, v37
	v_rcp_f32_e32 v32, v32
	v_rcp_f32_e32 v33, v33
	v_rcp_f32_e32 v28, v28
	v_rcp_f32_e32 v29, v29
	v_pk_mul_f32 v[20:21], v[24:25], v[20:21]
	v_pk_mul_f32 v[24:25], v[134:135], v[38:39] op_sel_hi:[1,0]
	v_pk_mul_f32 v[26:27], v[26:27], v[36:37]
	v_pk_mul_f32 v[20:21], v[20:21], v[24:25]
	v_pk_mul_f32 v[22:23], v[22:23], v[32:33]
	v_pk_mul_f32 v[20:21], v[20:21], v[28:29]
	v_add_u32_e32 v24, 0xa0, v128
	s_and_b64 vcc, exec, s[42:43]
	s_mov_b64 s[26:27], -1
	s_cbranch_vccnz .LBB0_323
	v_cvt_pk_fp8_f32 v28, v26, v27
	v_cvt_pk_fp8_f32 v29, v18, v19
	v_mad_u32_u24 v30, v24, s92, v132
	v_cvt_pk_fp8_f32 v28, v22, v23 op_sel:[0,0,1]
	v_cvt_pk_fp8_f32 v29, v20, v21 op_sel:[0,0,1]
	s_mov_b64 s[26:27], 0
	global_store_dwordx2 v30, v[28:29], s[8:9]
